# static priority: waves 4-7 run at s_setprio 1 for the whole kernel, no per-segment toggling in K-loops
# speedup vs baseline: 1.0060x; 1.0011x over previous
; #define LAS __attribute__((address_space(3)))
; __device__ __forceinline__ unsigned xb_add(unsigned* p, unsigned v) { return __hip_atomic_fetch_add(p, v, __ATOMIC_RELAXED, __HIP_MEMORY_SCOPE_AGENT); }
; __device__ __forceinline__ unsigned xb_xcc_id() { return (unsigned)__builtin_amdgcn_s_getreg((3 << 11) | 20) & 0xFu; }
; __device__ __forceinline__ XcdBarrier xcd_barrier_post(unsigned* bar, volatile LAS unsigned* st) {
;     XcdBarrier b; b.bar = bar; b.x = xb_xcc_id(); b.st = st;
;     if (threadIdx.x == 0) (void)xb_add(&bar[XB_XCNT(b.x)], 1u);
;     return b;
; __global__ void __launch_bounds__(NTHREADS, 2) fwd_megakernel(Params p) {
;     extern __shared__ __attribute__((aligned(16))) unsigned char lds_raw[];
;     LAS unsigned char* lds = (LAS unsigned char*)lds_raw;
;     const int G = gridDim.x, c = blockIdx.x;
;     volatile LAS unsigned* xst = (volatile LAS unsigned*)(lds + STAGE_BYTES);
;     unsigned* barw = (unsigned*)(p.ws + WS_BAR);
;     if (threadIdx.x < 2) xst[threadIdx.x] = 0u;
;     __syncthreads();
;     const XcdBarrier xb = xcd_barrier_post(barw, xst);
_Z14fwd_megakernel6Params:
	s_load_dwordx16 s[12:27], s[0:1], 0x40
	s_load_dword s33, s[0:1], 0x80
	s_mov_b32 s8, s2
	s_mov_b32 s101, 0
	v_readfirstlane_b32 s98, v0
	s_cmpk_gt_u32 s98, 0xff
	s_cbranch_scc0 .Lprio_skip
	s_setprio 1
.Lprio_skip:
	s_add_u32 s2, s0, 0x80
	s_addc_u32 s3, s1, 0
	v_cmp_gt_u32_e32 vcc, 2, v0
	v_writelane_b32 v230, s2, 0
	s_nop 1
	v_writelane_b32 v230, s3, 1
	s_and_saveexec_b64 s[2:3], vcc
	v_lshl_add_u32 v1, v0, 2, 0
	v_add_u32_e32 v1, 0x20000, v1
	v_mov_b32_e32 v2, 0
	ds_write_b32 v1, v2
	s_or_b64 exec, exec, s[2:3]
	s_load_dwordx16 s[36:51], s[0:1], 0x0
	s_waitcnt lgkmcnt(0)
	s_add_u32 s88, s26, 0x2f040000
	s_barrier
	s_getreg_b32 s0, hwreg(HW_REG_XCC_ID, 0, 4)
	s_addc_u32 s89, s27, 0
	s_and_b32 s0, s0, 15
	v_writelane_b32 v230, s0, 2
	v_cmp_eq_u32_e64 s[0:1], 0, v0
	s_mov_b64 s[2:3], exec
	s_nop 0
	v_writelane_b32 v230, s0, 3
	s_nop 1
	v_writelane_b32 v230, s1, 4
	s_and_b64 s[0:1], s[2:3], s[0:1]
	s_mov_b64 exec, s[0:1]
	s_cbranch_execz .LBB0_5
	s_mov_b64 s[4:5], exec
	v_mbcnt_lo_u32_b32 v1, s4, 0
	v_mbcnt_hi_u32_b32 v1, s5, v1
	v_cmp_eq_u32_e32 vcc, 0, v1
	s_and_b64 s[0:1], exec, vcc
	s_mov_b64 exec, s[0:1]
	s_cbranch_execz .LBB0_5
	v_readlane_b32 s0, v230, 2
	s_lshl_b32 s0, s0, 8
	s_bcnt1_i32_b64 s1, s[4:5]
	v_mov_b32_e32 v1, s0
	v_mov_b32_e32 v2, s1
	global_atomic_add v1, v2, s[88:89] offset:1024
